# w_out/w_up conversion run by the two attention waves at the START of the scan phase (HBM idle there), w_down in the up-projection tail, hand-written rwkv scanner loop, phase-3 load chains de-serialise
# speedup vs baseline: 1.0140x; 1.0140x over previous
.LBB0_518:
.LBB0_519:
	s_setprio 0
	s_cmp_lt_u32 s82, 6
	s_cbranch_scc1 .Ldc4_skip
	s_branch .Ldc4_entry
.Ldc4_ret:
	v_readfirstlane_b32 s82, v159
	s_lshr_b32 s82, s82, 6
.Ldc4_skip:
	s_add_i32 s0, s82, -6
	s_cmp_gt_u32 s0, -3
	s_cbranch_scc1 .LBB0_552
	s_mul_i32 s0, s82, 0x410
	s_add_i32 s48, s0, 0
	s_add_i32 s48, s48, 0x15040
	s_cmp_gt_i32 s82, 5
	v_readlane_b32 s0, v254, 39
	s_mulk_i32 s82, 0x4800
	s_cselect_b32 s0, s0, 0
	s_waitcnt vmcnt(12)
	v_lshrrev_b32_e32 v2, 5, v161
	v_and_b32_e32 v0, 7, v166
	s_add_i32 s0, s0, s82
	s_waitcnt vmcnt(1)
	v_and_b32_e32 v147, 31, v166
	v_lshrrev_b32_e32 v149, 3, v161
	v_lshlrev_b32_e32 v148, 3, v0
	v_lshlrev_b32_e32 v0, 4, v0
	v_or_b32_e32 v5, 32, v161
	v_lshlrev_b32_e32 v150, 2, v2
	s_getreg_b32 s49, hwreg(HW_REG_XCC_ID, 0, 4)
	v_lshlrev_b32_e32 v146, 3, v2
	v_add_u32_e32 v3, s0, v0
	v_mul_u32_u24_e32 v4, 0x90, v149
	v_mul_u32_u24_e32 v225, 0x90, v5
	v_and_b32_e32 v226, 15, v166
	v_mov_b32_e32 v5, 0x4000
	v_lshl_or_b32 v233, v147, 9, v150
	s_mov_b32 s50, 0
	v_cmp_eq_u32_e64 s[38:39], 0, v161
	v_lshl_add_u32 v151, v2, 4, s0
	v_add_u32_e32 v167, s0, v146
	v_mul_u32_u24_e32 v224, 0x90, v147
	v_cmp_gt_u32_e64 s[0:1], 16, v147
	v_lshl_or_b32 v227, v161, 9, v5
	v_lshl_add_u64 v[152:153], s[6:7], 0, v[0:1]
	v_or_b32_e32 v228, 0xffffffc0, v161
	v_lshl_add_u32 v229, v161, 2, s48
	v_mad_i32_i24 v230, v2, -4, v147
	v_sub_u32_e32 v231, v226, v150
	v_or_b32_e32 v232, 59, v150
	v_or_b32_e32 v234, 48, v233
	v_or_b32_e32 v235, 32, v233
	v_or_b32_e32 v236, 16, v233
	v_lshl_or_b32 v237, v147, 10, v146
	v_add_u32_e32 v238, v3, v4
	s_mov_b32 s51, s49
	s_mov_b32 s76, s18
	s_branch .LBB0_522
